# start-up grid barrier in two levels (8 groups of 64 workgroups, separate lines for counters and release flags) instead of one 512-way counter
# speedup vs baseline: 1.0066x; 1.0038x over previous
; #define LAS __attribute__((address_space(3)))
; __global__ void __launch_bounds__(256, 2) k_mega(Params p) {
;   __shared__ __attribute__((aligned(16))) char lds[LDS_BYTES];
;   __shared__ uint4 xb_words;
;   cg::grid_group grid = cg::this_grid();
;   if (threadIdx.x == 0) xb_words = make_uint4(0u, 0u, 0u, 0u);
;   __syncthreads();
;   const XcdBarrier xb = xcd_barrier_post(p.bar, (volatile LAS unsigned*)&xb_words);
;   phase_norm0(p, lds);
;   grid.sync();
; #pragma unroll 1
;   for (int l = 0; l < NL; ++l) {
;     phase_gemm_in(p, l, lds); xcd_barrier(xb);
;     phase_chunk(p, l, lds); xcd_barrier(xb);
;     phase_mix(p, l, lds); xcd_barrier(xb);
;     phase_o(p, l, blockIdx.x, NCH_P / 2, gridDim.x); xcd_barrier(xb);
;     phase_merge(p, l, lds); xcd_barrier(xb);
;     phase_out(p, l, lds); xcd_barrier(xb);
;     phase_ple(p, l, lds); if (l + 1 < NL) xcd_barrier(xb);
.LBB0_50:
	s_waitcnt lgkmcnt(0)
	s_load_dwordx16 s[68:83], s[0:1], 0x80
	v_readlane_b32 s26, v251, 0
	s_sub_i32 s2, s26, 32
	s_cmp_lt_i32 s26, 32
	s_cselect_b64 s[0:1], -1, 0
	s_waitcnt lgkmcnt(0)
	v_writelane_b32 v252, s68, 3
	s_and_b64 s[0:1], s[0:1], exec
	s_cselect_b32 s20, s26, s2
	v_writelane_b32 v252, s69, 4
	v_writelane_b32 v252, s70, 5
	v_writelane_b32 v252, s71, 6
	v_writelane_b32 v252, s72, 7
	v_writelane_b32 v252, s73, 8
	v_writelane_b32 v252, s74, 9
	v_writelane_b32 v252, s75, 10
	v_writelane_b32 v252, s76, 11
	v_writelane_b32 v252, s77, 12
	v_writelane_b32 v252, s78, 13
	v_writelane_b32 v252, s79, 14
	v_writelane_b32 v252, s80, 15
	s_lshl_b32 s0, s20, 1
	v_writelane_b32 v252, s81, 16
	s_lshl_b32 s28, s26, 7
	s_add_i32 s2, s0, 0x1000
	v_writelane_b32 v252, s82, 17
	s_cmp_lt_i32 s26, 32
	v_writelane_b32 v252, s83, 18
	s_cselect_b64 s[0:1], -1, 0
	v_writelane_b32 v252, s0, 19
	v_readlane_b32 s68, v251, 49
	v_readlane_b32 s70, v251, 51
	v_writelane_b32 v252, s1, 20
	s_and_b64 s[0:1], s[0:1], exec
	s_cselect_b32 s24, 0x80, 2
	s_cselect_b32 s96, s28, s2
	s_lshr_b32 s21, s26, 3
	s_lshr_b32 s27, s90, 3
	s_cmp_lt_u32 s21, s27
	s_cselect_b64 s[2:3], -1, 0
	s_and_b32 s29, s26, 7
	s_mul_i32 s0, s29, 0x1944
	s_lshr_b32 s1, s0, 3
	s_addk_i32 s0, 0x1944
	s_lshr_b32 s31, s0, 3
	s_add_i32 s34, s1, s21
	s_cmp_lt_u32 s34, s31
	s_cselect_b64 s[0:1], -1, 0
	v_writelane_b32 v252, s29, 21
	s_and_b64 s[0:1], s[2:3], s[0:1]
	v_writelane_b32 v252, s0, 22
	v_readlane_b32 s71, v251, 52
	v_readlane_b32 s69, v251, 50
	v_writelane_b32 v252, s1, 23
	s_add_u32 s0, s70, 0x1481a000
	v_readlane_b32 s83, v252, 0
	v_writelane_b32 v252, s0, 24
	s_addc_u32 s0, s71, 0
	v_writelane_b32 v252, s0, 25
	s_add_u32 s0, s70, 0xc200000
	v_writelane_b32 v252, s0, 26
	s_addc_u32 s0, s71, 0
	v_writelane_b32 v252, s0, 27
	s_add_u32 s0, s70, 0x1441a000
	v_writelane_b32 v252, s0, 28
	s_addc_u32 s0, s71, 0
	v_writelane_b32 v252, s0, 29
	s_add_u32 s0, s70, 0x4200000
	v_writelane_b32 v252, s0, 30
	s_addc_u32 s0, s71, 0
	v_writelane_b32 v252, s0, 31
	s_add_u32 s0, s70, 0x1501a000
	s_addc_u32 s1, s71, 0
	v_writelane_b32 v252, s0, 32
	v_readlane_b32 s72, v251, 53
	v_readlane_b32 s73, v251, 54
	v_writelane_b32 v252, s1, 33
	s_add_u32 s0, s70, 0x14400000
	v_writelane_b32 v252, s0, 34
	s_addc_u32 s0, s71, 0
	v_writelane_b32 v252, s0, 35
	s_lshl_b32 s0, s26, 8
	s_lshl_b32 s35, s90, 8
	s_cmpk_lt_i32 s26, 0x140
	v_writelane_b32 v252, s0, 36
	s_cselect_b64 s[0:1], -1, 0
	s_add_u32 s92, s66, 0x200
	s_addc_u32 s93, s67, 0
	s_add_u32 s22, s66, 0x1000
	s_addc_u32 s23, s67, 0
	v_writelane_b32 v252, s22, 37
	v_readlane_b32 s74, v251, 55
	v_readlane_b32 s75, v251, 56
	v_writelane_b32 v252, s23, 38
	s_add_u32 s22, s66, 0x1100
	s_addc_u32 s23, s67, 0
	v_writelane_b32 v252, s22, 39
	v_readlane_b32 s76, v251, 57
	v_readlane_b32 s77, v251, 58
	v_writelane_b32 v252, s23, 40
	s_add_u32 s22, s66, 0x1200
	s_addc_u32 s23, s67, 0
	v_writelane_b32 v252, s22, 41
	v_readlane_b32 s78, v251, 59
	v_readlane_b32 s79, v251, 60
	v_writelane_b32 v252, s23, 42
	s_add_u32 s22, s66, 0x1300
	s_addc_u32 s23, s67, 0
	v_writelane_b32 v252, s22, 43
	s_cmp_eq_u32 s36, 15
	v_readlane_b32 s80, v251, 61
	v_writelane_b32 v252, s23, 44
	s_cselect_b64 s[22:23], -1, 0
	v_writelane_b32 v252, s22, 45
	s_cmp_eq_u32 s36, 14
	v_readlane_b32 s81, v251, 62
	v_writelane_b32 v252, s23, 46
	s_cselect_b64 s[22:23], -1, 0
	v_writelane_b32 v252, s22, 47
	s_cmp_eq_u32 s36, 13
	v_readlane_b32 s82, v251, 63
	v_writelane_b32 v252, s23, 48
	s_cselect_b64 s[22:23], -1, 0
	v_writelane_b32 v252, s22, 49
	s_cmp_eq_u32 s36, 12
	v_readlane_b32 s68, v251, 17
	v_writelane_b32 v252, s23, 50
	s_cselect_b64 s[22:23], -1, 0
	v_writelane_b32 v252, s22, 51
	s_cmp_eq_u32 s36, 11
	v_readlane_b32 s74, v251, 23
	v_writelane_b32 v252, s23, 52
	s_cselect_b64 s[22:23], -1, 0
	v_writelane_b32 v252, s22, 53
	s_cmp_eq_u32 s36, 10
	v_readlane_b32 s75, v251, 24
	v_writelane_b32 v252, s23, 54
	s_cselect_b64 s[22:23], -1, 0
	v_writelane_b32 v252, s22, 55
	s_cmp_eq_u32 s36, 9
	v_readlane_b32 s82, v251, 31
	v_writelane_b32 v252, s23, 56
	s_cselect_b64 s[22:23], -1, 0
	v_writelane_b32 v252, s22, 57
	s_cmp_eq_u32 s36, 8
	v_readlane_b32 s83, v251, 32
	v_writelane_b32 v252, s23, 58
	s_cselect_b64 s[22:23], -1, 0
	v_writelane_b32 v252, s22, 59
	s_cmp_eq_u32 s36, 7
	v_readlane_b32 s78, v251, 27
	v_writelane_b32 v252, s23, 60
	s_cselect_b64 s[22:23], -1, 0
	v_writelane_b32 v252, s22, 61
	s_cmp_eq_u32 s36, 6
	v_readlane_b32 s79, v251, 28
	v_writelane_b32 v252, s23, 62
	s_cselect_b64 s[22:23], -1, 0
	v_writelane_b32 v252, s22, 63
	s_cmp_eq_u32 s36, 5
	s_mov_b32 s97, 0
	v_writelane_b32 v253, s23, 0
	s_cselect_b64 s[22:23], -1, 0
	v_writelane_b32 v253, s22, 1
	s_cmp_eq_u32 s36, 4
	v_readlane_b32 s69, v251, 18
	v_writelane_b32 v253, s23, 2
	s_cselect_b64 s[22:23], -1, 0
	v_writelane_b32 v253, s22, 3
	s_cmp_eq_u32 s36, 3
	v_readlane_b32 s70, v251, 19
	v_writelane_b32 v253, s23, 4
	s_cselect_b64 s[22:23], -1, 0
	v_writelane_b32 v253, s22, 5
	s_cmp_eq_u32 s36, 2
	v_readlane_b32 s71, v251, 20
	v_writelane_b32 v253, s23, 6
	s_cselect_b64 s[22:23], -1, 0
	v_writelane_b32 v253, s22, 7
	s_cmp_eq_u32 s36, 1
	v_readlane_b32 s72, v251, 21
	v_writelane_b32 v253, s23, 8
	s_cselect_b64 s[22:23], -1, 0
	v_writelane_b32 v253, s22, 9
	s_cmp_eq_u32 s36, 0
	v_readlane_b32 s73, v251, 22
	v_writelane_b32 v253, s23, 10
	s_cselect_b64 s[22:23], -1, 0
	v_writelane_b32 v253, s22, 11
	v_readlane_b32 s76, v251, 25
	v_readlane_b32 s77, v251, 26
	v_writelane_b32 v253, s23, 12
	s_lshl_b32 s22, s36, 8
	s_add_u32 s22, s66, s22
	s_addc_u32 s23, s67, 0
	s_add_u32 s36, s22, 0x1400
	s_addc_u32 s37, s23, 0
	v_writelane_b32 v253, s36, 13
; DI int tid_() { int t = threadIdx.x; asm volatile("" : "+v"(t)); return t; }
; DI void rec_item(const Params& p, int l, int item, char* lds) {
;   const int tid = tid_(), wave = __builtin_amdgcn_readfirstlane(tid >> 6), lane = tid & 63, l15 = lane & 15, quad = lane >> 4;
;   const bool isp = item < 32;
;   const int bh = isp ? item : item - 32; const int b = bh >> 3, h = bh & 7;
;   const int nch = isp ? 128 : 2; const int cid0 = isp ? bh * 128 : NCH_P + bh * 2;
; DI void phase_mix(const Params& p, int l, char* lds) {
;   __shared__ int s_next;
;   if (blockIdx.x < 96) {
;     if (blockIdx.x >= 32) {
;       for (int c2 = 0; c2 < 2; ++c2) chunk_item(p, l, NCH_P + (blockIdx.x - 32) * 2 + c2, lds);
;       __syncthreads();
;     }
;     __builtin_amdgcn_s_setprio(3); rec_item(p, l, blockIdx.x, lds); __builtin_amdgcn_s_setprio(0);
;     if (blockIdx.x >= 32) { const int pis = NCH_P / 2 + (blockIdx.x - 32); phase_o(p, l, pis, pis + 1, 1); }
	s_add_u32 s22, s22, 0x2400
	s_addc_u32 s23, s23, 0
	v_writelane_b32 v253, s37, 14
	v_writelane_b32 v253, s22, 15
	v_readlane_b32 s36, v252, 3
	v_readlane_b32 s38, v252, 5
	v_writelane_b32 v253, s23, 16
	s_add_u32 s22, s66, 0x3400
	s_addc_u32 s23, s67, 0
	v_writelane_b32 v253, s22, 17
	v_readlane_b32 s39, v252, 6
	v_readlane_b32 s37, v252, 4
	v_writelane_b32 v253, s23, 18
	s_add_u32 s22, s66, 0x3500
	s_addc_u32 s23, s67, 0
	v_writelane_b32 v253, s22, 19
	s_cmpk_lt_i32 s26, 0x1000
	v_readlane_b32 s42, v252, 9
	v_writelane_b32 v253, s23, 20
	s_cselect_b64 s[22:23], -1, 0
	v_writelane_b32 v253, s22, 21
	s_cmpk_lt_u32 s26, 0x60
	v_readlane_b32 s43, v252, 10
	v_writelane_b32 v253, s23, 22
	s_cselect_b64 s[22:23], -1, 0
	v_writelane_b32 v253, s22, 23
	s_cmp_gt_u32 s26, 31
	v_readlane_b32 s80, v251, 29
	v_writelane_b32 v253, s23, 24
	s_cselect_b64 s[22:23], -1, 0
	v_writelane_b32 v253, s22, 25
	s_lshl_b32 s25, s26, 1
	v_readlane_b32 s81, v251, 30
	v_writelane_b32 v253, s23, 26
	s_sub_i32 s22, s25, 64
	s_lshr_b32 s23, s22, 4
	v_writelane_b32 v253, s23, 27
	s_lshl_b32 s23, s23, 6
	s_addk_i32 s23, 0x4000
	s_lshl_b32 s22, s22, 5
	v_writelane_b32 v253, s23, 28
	s_and_b32 s22, s22, 0x1c0
	s_add_i32 s23, s25, 0xfc0
	v_writelane_b32 v253, s23, 29
	s_lshl_b32 s23, s22, 7
	v_writelane_b32 v253, s23, 30
	v_writelane_b32 v253, s22, 31
	s_lshl_b32 s22, s22, 2
	s_add_u32 s23, s74, s22
	v_writelane_b32 v253, s23, 32
	s_addc_u32 s23, s75, 0
	v_writelane_b32 v253, s23, 33
	s_add_u32 s23, s82, s22
	v_writelane_b32 v253, s23, 34
	s_addc_u32 s23, s83, 0
	v_writelane_b32 v253, s23, 35
	s_add_u32 s23, s38, s22
	v_writelane_b32 v253, s23, 36
	s_addc_u32 s23, s39, 0
	v_writelane_b32 v253, s23, 37
	s_add_u32 s23, s78, s22
	v_writelane_b32 v253, s23, 38
	s_addc_u32 s23, s79, 0
	v_writelane_b32 v253, s23, 39
	s_add_u32 s23, s36, s22
	v_writelane_b32 v253, s23, 40
	s_addc_u32 s23, s37, 0
	v_writelane_b32 v253, s23, 41
	s_add_u32 s22, s42, s22
	v_writelane_b32 v253, s22, 42
	s_addc_u32 s22, s43, 0
	s_cmp_gt_i32 s26, 31
	v_writelane_b32 v253, s22, 43
	s_cselect_b64 s[22:23], -1, 0
	v_writelane_b32 v253, s22, 44
	v_readlane_b32 s68, v251, 49
	v_readlane_b32 s72, v251, 53
	v_writelane_b32 v253, s23, 45
	s_ashr_i32 s22, s20, 3
	s_lshl_b32 s20, s20, 6
	v_writelane_b32 v253, s22, 46
	s_and_b32 s36, s20, 0x1c0
	s_lshl_b64 s[22:23], s[96:97], 13
	s_add_u32 s38, s88, s22
	s_addc_u32 s39, s89, s23
	v_writelane_b32 v253, s38, 47
	s_add_i32 s20, s24, -2
	s_add_i32 s24, s24, -1
	v_writelane_b32 v253, s39, 48
	s_add_u32 s38, s56, s22
	v_writelane_b32 v253, s20, 49
	s_addc_u32 s39, s57, s23
	v_writelane_b32 v253, s38, 50
	s_add_u32 s22, s58, s22
	s_addc_u32 s23, s59, s23
	v_writelane_b32 v253, s39, 51
	v_writelane_b32 v253, s22, 52
	v_readlane_b32 s73, v251, 54
	s_mov_b32 s37, s97
	v_writelane_b32 v253, s23, 53
	s_or_b32 s22, s96, 1
	s_mov_b32 s23, s97
	s_lshl_b64 s[22:23], s[22:23], 13
	s_add_u32 s38, s56, s22
	s_addc_u32 s39, s57, s23
	s_add_u32 s22, s58, s22
	v_writelane_b32 v253, s38, 54
	s_addc_u32 s23, s59, s23
	s_min_u32 s20, s24, 2
	v_writelane_b32 v253, s39, 55
	s_or_b32 s20, s20, s28
	v_writelane_b32 v253, s22, 56
	s_lshl_b32 s20, s20, 13
	v_readlane_b32 s78, v251, 59
	v_writelane_b32 v253, s23, 57
	s_add_u32 s22, s58, s20
	s_addc_u32 s23, s59, 0
	v_writelane_b32 v253, s22, 58
	v_readlane_b32 s79, v251, 60
	v_readlane_b32 s82, v251, 63
	v_writelane_b32 v253, s23, 59
	s_add_u32 s22, s56, s20
	s_addc_u32 s23, s57, 0
	v_writelane_b32 v253, s22, 60
	v_readlane_b32 s83, v252, 0
	v_readlane_b32 s49, v252, 16
	v_writelane_b32 v253, s23, 61
	s_add_i32 s22, s96, s24
	s_mov_b32 s23, s97
	s_lshl_b64 s[22:23], s[22:23], 13
	s_add_u32 s22, s88, s22
	v_writelane_b32 v253, s24, 62
	s_addc_u32 s23, s89, s23
	v_writelane_b32 v253, s22, 63
	s_mov_b32 s49, s27
	v_readlane_b32 s50, v252, 17
	v_writelane_b32 v254, s23, 0
	s_add_u32 s22, s88, 0x2100000
	s_addc_u32 s23, s89, 0
	v_writelane_b32 v254, s22, 1
	s_sub_i32 s20, 64, s25
	s_cmpk_lg_i32 s90, 0x200
	v_writelane_b32 v254, s23, 2
	v_writelane_b32 v254, s25, 3
	v_writelane_b32 v254, s20, 4
	s_cselect_b64 s[22:23], -1, 0
	s_and_b32 s20, s26, 0xffffffe0
	s_cmpk_lg_i32 s20, 0x100
	s_cselect_b64 s[24:25], -1, 0
	s_or_b64 s[22:23], s[24:25], s[22:23]
	s_lshl_b32 s20, s29, 2
	v_writelane_b32 v254, s22, 5
	s_add_u32 s20, s66, s20
	v_readlane_b32 s51, v252, 18
	v_writelane_b32 v254, s23, 6
	s_addc_u32 s22, s67, 0
	s_add_u32 s20, s20, 0x3600
	v_writelane_b32 v254, s20, 7
	s_addc_u32 s20, s22, 0
	s_cmpk_lt_i32 s26, 0x800
	v_writelane_b32 v254, s20, 8
	s_cselect_b64 s[22:23], -1, 0
	s_lshl_b32 s20, s29, 7
	s_add_i32 s38, s20, s21
	s_lshl_b32 s20, s29, 10
	s_addk_i32 s20, 0x400
	v_writelane_b32 v254, s22, 9
	s_lshr_b32 s20, s20, 3
	s_cmp_lt_u32 s38, s20
	v_writelane_b32 v254, s23, 10
	v_writelane_b32 v254, s20, 11
	s_cselect_b64 s[20:21], -1, 0
	s_and_b64 s[2:3], s[2:3], s[20:21]
	v_writelane_b32 v254, s2, 12
	s_cmpk_lt_i32 s26, 0x200
	s_mov_b32 s29, s97
	v_writelane_b32 v254, s3, 13
	s_mul_i32 s2, s91, s90
	s_mul_i32 s2, s2, s33
	v_writelane_b32 v254, s2, 14
	s_cselect_b64 s[2:3], -1, 0
	v_writelane_b32 v254, s2, 15
	s_cmpk_lt_i32 s26, 0x1030
; #define LAS __attribute__((address_space(3)))
; __global__ void __launch_bounds__(256, 2) k_mega(Params p) {
;     ...
;   cg::grid_group grid = cg::this_grid();
;   if (threadIdx.x == 0) xb_words = make_uint4(0u, 0u, 0u, 0u);
;   __syncthreads();
;   const XcdBarrier xb = xcd_barrier_post(p.bar, (volatile LAS unsigned*)&xb_words);
;   phase_norm0(p, lds);
;   grid.sync();
	v_readlane_b32 s45, v252, 12
	v_writelane_b32 v254, s3, 16
	s_cselect_b64 s[2:3], -1, 0
	v_writelane_b32 v254, s2, 17
	v_readlane_b32 s50, v252, 1
	v_mov_b32_e32 v1, 0
	v_writelane_b32 v254, s3, 18
	s_add_u32 s2, s8, 0x80
	s_addc_u32 s3, s9, 0
	v_writelane_b32 v254, s2, 19
	v_mov_b32_e32 v249, 0x358637bd
	v_mov_b32_e32 v210, 0x12000
	v_writelane_b32 v254, s3, 20
	s_add_u32 s2, s72, 0x80
	s_addc_u32 s3, s73, 0
	v_writelane_b32 v254, s2, 21
	v_mov_b32_e32 v211, 0x12004
	v_mbcnt_hi_u32_b32 v218, -1, v213
	v_writelane_b32 v254, s3, 22
	v_writelane_b32 v254, s28, 23
	s_add_i32 s2, s96, 2
	v_mov_b32_e32 v219, 0x260
	v_writelane_b32 v254, s29, 24
	v_writelane_b32 v254, s2, 25
	s_lshl_b64 s[2:3], s[28:29], 13
	s_add_u32 s2, s88, s2
	s_addc_u32 s3, s89, s3
	s_add_u32 s2, s2, 0x2040
	s_addc_u32 s3, s3, 0
	v_writelane_b32 v254, s2, 26
	v_mov_b32_e32 v221, 0x12010
	v_mov_b32_e32 v250, 0x4000
	v_writelane_b32 v254, s3, 27
	v_writelane_b32 v254, s36, 28
	s_or_b32 s2, s28, 3
	v_mov_b32_e32 v220, 0x6000
	v_writelane_b32 v254, s37, 29
	v_writelane_b32 v254, s2, 30
	s_add_u32 s2, s18, 0x80
	v_writelane_b32 v254, s2, 31
	s_addc_u32 s2, s19, 0
	v_writelane_b32 v254, s2, 32
	s_lshl_b32 s2, s90, 1
	v_writelane_b32 v254, s2, 33
	s_lshl_b32 s3, s26, 5
	s_lshl_b32 s2, s90, 5
	s_add_u32 s20, s78, 0x80
	v_writelane_b32 v254, s2, 34
	s_addc_u32 s21, s79, 0
	v_writelane_b32 v254, s20, 35
	v_mov_b32_e32 v248, 0x400
	v_mov_b32_e32 v230, 0x41b17218
	v_writelane_b32 v254, s21, 36
	s_add_u32 s20, s52, 0x80
	s_addc_u32 s21, s53, 0
	v_writelane_b32 v254, s20, 37
	v_mov_b32_e32 v231, 0x100000
	v_mov_b32_e32 v160, 0x3e38aa3b
	v_writelane_b32 v254, s21, 38
	s_add_u32 s20, s82, 0x80
	s_addc_u32 s21, s83, 0
	v_writelane_b32 v254, s20, 39
	s_lshl_b32 s2, s26, 12
	s_add_i32 s2, s2, 0xff7d0000
	v_writelane_b32 v254, s21, 40
	v_writelane_b32 v254, s2, 41
	s_lshl_b32 s2, s26, 2
	s_addk_i32 s2, 0xcf40
	v_writelane_b32 v254, s2, 42
	s_lshl_b32 s2, s26, 3
	s_addk_i32 s2, 0x9e80
	v_writelane_b32 v254, s2, 43
	s_xor_b64 s[0:1], s[0:1], -1
	v_writelane_b32 v254, s0, 44
	s_movk_i32 s91, 0x4000
	s_mov_b32 s33, 0x8000
	v_writelane_b32 v254, s1, 45
	v_writelane_b32 v254, s3, 46
	s_add_i32 s0, s3, 0xfffefa00
	v_writelane_b32 v254, s0, 47
	s_lshl_b32 s0, s26, 6
	v_writelane_b32 v254, s0, 48
	s_lshl_b32 s0, s90, 6
	v_writelane_b32 v254, s0, 49
	s_lshl_b32 s0, s90, 12
	v_writelane_b32 v254, s0, 50
	s_lshl_b32 s0, s90, 2
	s_mov_b64 s[20:21], s[84:85]
	v_writelane_b32 v254, s0, 51
	s_mov_b64 s[22:23], s[86:87]
	s_mov_b64 s[24:25], s[88:89]
	s_mov_b32 s26, s90
	v_writelane_b32 v254, s20, 52
	s_lshl_b32 s0, s90, 3
	s_mov_b32 s87, s38
	v_writelane_b32 v254, s21, 53
	v_writelane_b32 v254, s22, 54
	v_writelane_b32 v254, s23, 55
	v_writelane_b32 v254, s24, 56
	v_writelane_b32 v254, s25, 57
	v_writelane_b32 v254, s26, 58
	v_writelane_b32 v254, s27, 59
	v_writelane_b32 v254, s0, 60
	v_writelane_b32 v254, s92, 61
	s_mov_b32 s86, s35
	s_mov_b32 s85, s34
	s_mov_b32 s84, s31
	s_mov_b32 s34, 0x800000
	s_movk_i32 s94, 0x3100
	s_movk_i32 s45, 0x41ff
	s_movk_i32 s90, 0x90
	s_movk_i32 s95, 0x50
	s_mov_b32 s35, 0x3e38aa3b
	s_mov_b64 s[28:29], 0x80
	s_mov_b64 s[88:89], 0x380
	s_mov_b32 s20, s97
	v_readlane_b32 s51, v252, 2
	v_writelane_b32 v254, s93, 62
	v_readlane_b32 s40, v252, 7
	v_readlane_b32 s41, v252, 8
	v_readlane_b32 s44, v252, 11
	v_readlane_b32 s46, v252, 13
	v_readlane_b32 s47, v252, 14
	v_readlane_b32 s48, v252, 15
	v_readlane_b32 s69, v251, 50
	v_readlane_b32 s70, v251, 51
	v_readlane_b32 s71, v251, 52
	v_readlane_b32 s74, v251, 55
	v_readlane_b32 s75, v251, 56
	v_readlane_b32 s76, v251, 57
	v_readlane_b32 s77, v251, 58
	v_readlane_b32 s80, v251, 61
	v_readlane_b32 s81, v251, 62
	s_waitcnt vmcnt(0) lgkmcnt(0)
	s_barrier
	s_and_saveexec_b64 s[0:1], s[50:51]
	s_cbranch_execz .Lgsync_done
	buffer_wbl2 sc1
	s_waitcnt vmcnt(0)
	v_readlane_b32 s21, v252, 21
	v_mov_b32_e32 v2, 1
	s_nop 1
	s_lshl_b32 s21, s21, 8
	s_add_u32 s24, s66, s21
	s_addc_u32 s25, s67, 0
	s_add_u32 s26, s24, 0x2480
	s_addc_u32 s27, s25, 0
	s_add_u32 s24, s24, 0x1480
	s_addc_u32 s25, s25, 0
	global_atomic_add v0, v1, v2, s[24:25] sc0
	s_mov_b32 s21, 0
	s_waitcnt vmcnt(0)
	v_readfirstlane_b32 s22, v0
	s_nop 3
	s_cmp_lg_u32 s22, 63
	s_cbranch_scc1 .Lgsync_spin
	s_add_u32 s22, s66, 0x3480
	s_addc_u32 s23, s67, 0
	global_atomic_add v0, v1, v2, s[22:23] sc0
	s_waitcnt vmcnt(0)
	v_readfirstlane_b32 s22, v0
	s_nop 3
	s_cmp_lg_u32 s22, 7
	s_cbranch_scc1 .Lgsync_spin
	s_add_u32 s22, s66, 0x2480
	s_addc_u32 s23, s67, 0
	global_atomic_add v1, v2, s[22:23]
	global_atomic_add v1, v2, s[22:23] offset:256
	global_atomic_add v1, v2, s[22:23] offset:512
	global_atomic_add v1, v2, s[22:23] offset:768
	global_atomic_add v1, v2, s[22:23] offset:1024
	global_atomic_add v1, v2, s[22:23] offset:1280
	global_atomic_add v1, v2, s[22:23] offset:1536
	global_atomic_add v1, v2, s[22:23] offset:1792
	s_waitcnt vmcnt(0)
.Lgsync_spin:
	global_load_dword v0, v1, s[26:27] sc1
	s_waitcnt vmcnt(0)
	v_readfirstlane_b32 s22, v0
	s_nop 3
	s_cmp_lg_u32 s22, 0
	s_cbranch_scc1 .Lgsync_arrived
	s_sleep 1
	s_add_i32 s21, s21, 1
	s_cmp_lt_u32 s21, 0x400000
	s_cbranch_scc1 .Lgsync_spin
